# post-W_o grid barrier -> XCD-local barrier for layers 1-3 in local mode (on top of stagger afterX)
# speedup vs baseline: 1.0113x; 1.0113x over previous
.Lwo_local:
	s_waitcnt vmcnt(0)
	s_waitcnt lgkmcnt(0)
	s_barrier
	s_and_saveexec_b64 s[2:3], s[20:21]
	s_cbranch_execz .LBB0_1094
	v_readlane_b32 s0, v248, 15
	s_waitcnt vmcnt(0) expcnt(0) lgkmcnt(0)
	s_mov_b64 s[6:7], exec
	v_mov_b32_e32 v0, s0
	ds_read_b32 v2, v0
	v_mbcnt_lo_u32_b32 v0, s6, 0
	v_mbcnt_hi_u32_b32 v0, s7, v0
	v_cmp_eq_u32_e32 vcc, 0, v0
	s_and_saveexec_b64 s[8:9], vcc
	s_cbranch_execz .Lwol_185
	s_bcnt1_i32_b64 s0, s[6:7]
	v_readlane_b32 s6, v250, 19
	v_mov_b32_e32 v3, s0
	v_readlane_b32 s7, v250, 20
	s_nop 4
	global_atomic_add v3, v1, v3, s[6:7] sc0

.Lwol_189:

	s_and_b32 s4, s0, 0xff
	s_mov_b64 s[14:15], -1
	s_cmp_lg_u32 s4, 0
	s_mov_b64 s[18:19], -1
	s_sleep 1
	s_cbranch_scc1 .Lwol_192
	global_load_dword v2, v1, s[34:35] sc1
	s_waitcnt vmcnt(0)
	v_cmp_eq_u32_e32 vcc, 0, v2
	s_cbranch_vccnz .Lwol_194
	s_mov_b64 s[18:19], 0
	s_mov_b64 s[16:17], -1

.Lwol_199:
	s_or_b64 exec, exec, s[6:7]
	s_waitcnt vmcnt(0)
	buffer_inv sc1
	s_waitcnt vmcnt(0)
	s_branch .LBB0_1094

.LBB0_1042:
	v_readlane_b32 s0, v248, 31
	v_readlane_b32 s2, v251, 23
	v_readlane_b32 s3, v251, 24
	s_nop 3
	s_cmp_eq_u32 s0, 0
	s_cbranch_scc1 .Lwo_global
	s_and_b64 vcc, exec, s[2:3]
	s_cbranch_vccnz .Lwo_local
